# v41 + attention phases: static wave-half priority (waves 4-7 one level above waves 0-3), reset at phase exit
# baseline (speedup 1.0000x reference)
.LBB0_890:
	v_writelane_b32 v249, s4, 58
	s_add_u32 s52, s82, 0x32100000
	s_addc_u32 s53, s83, 0
	v_writelane_b32 v249, s5, 59
	v_lshrrev_b32_e32 v2, 2, v0
	v_readlane_b32 s0, v249, 45
	s_cmp_lt_u32 s0, 4
	s_cbranch_scc1 .Lattp_e
	s_setprio 3
.Lattp_e:
	s_lshl_b32 s2, s0, 5
	s_add_i32 s3, s2, 0x1000
	s_lshl_b32 s0, s0, 10
	s_add_u32 s20, s82, 0x38d00000
	s_addc_u32 s21, s83, 0
	s_add_u32 s22, s82, 0x3b100000
	s_addc_u32 s23, s83, 0
	s_add_u32 s24, s82, 0x37500000
	s_addc_u32 s25, s83, 0
	s_add_u32 s26, s82, 0x3a100000
	v_and_b32_e32 v186, 8, v2
	v_readlane_b32 s4, v249, 54
	s_addc_u32 s27, s83, 0
	s_add_i32 s54, s0, 0
	v_mov_b32_e32 v3, 0
	v_lshlrev_b32_e32 v182, 4, v194
	v_lshlrev_b32_e32 v2, 1, v186
	v_readlane_b32 s5, v249, 55
	s_add_i32 s55, s54, 0xa000
	s_add_i32 s0, 0, 0xa000
	v_lshl_add_u64 v[198:199], s[4:5], 0, v[2:3]
	v_add_u32_e32 v197, s0, v182
	s_add_i32 s0, 0, 0x14000
	v_mbcnt_lo_u32_b32 v2, -1, 0
	s_add_i32 s12, s55, 0x6000
	v_and_b32_e32 v1, 31, v0
	v_lshlrev_b32_e32 v192, 4, v0
	v_mov_b32_e32 v193, v3
	v_add_u32_e32 v195, 0, v182
	v_add_u32_e32 v204, s0, v182
	s_movk_i32 s28, 0x600
	s_mov_b64 s[0:1], 0x2000
	s_add_i32 s56, s54, 0x2000
	s_mov_b64 s[4:5], 0x4000
	s_add_i32 s57, s54, 0x4000
	s_add_i32 s58, s54, 0x6000
	s_add_i32 s59, s54, 0x8000
	s_mov_b64 s[6:7], 0x6000
	s_mov_b64 s[8:9], 0x8000
	s_add_i32 s60, s54, 0xc000
	s_mov_b64 s[10:11], 0xa000
	s_add_i32 s61, s54, 0xe000
	s_mov_b32 s29, 0xf149f2ca
	s_mov_b32 s30, 0x3dd53b94
	v_mbcnt_hi_u32_b32 v183, -1, v2
	s_mov_b32 s31, 0x41000000
	v_writelane_b32 v249, s12, 60
	s_add_i32 s63, s55, 0x8000
	s_add_i32 s64, s54, 0x14000
	s_add_i32 s65, s54, 0x16000
	s_add_i32 s47, s54, 0x18000
	s_add_i32 s48, s54, 0x1a000
	s_add_i32 s49, s54, 0x1c000
	v_writelane_b32 v249, s33, 61
	s_branch .LBB0_892

.LBB0_1053:
	s_setprio 2
	s_waitcnt vmcnt(0) lgkmcnt(0)
	s_waitcnt vmcnt(0)
	s_barrier

.LBB0_2170:
	s_add_u32 s8, s82, 0x32100000
	s_addc_u32 s9, s83, 0
	s_cmpk_gt_i32 s2, 0x1ff
	v_and_b32_e32 v211, 31, v0
	v_lshlrev_b32_e32 v212, 4, v194
	s_cbranch_scc1 .LBB0_2265
	v_readlane_b32 s1, v249, 45
	s_cmp_lt_u32 s1, 4
	s_cbranch_scc1 .Lattp_o
	s_setprio 3
.Lattp_o:
	s_lshl_b32 s0, s1, 5
	s_lshr_b32 s3, s88, 7
	s_and_b32 s21, s0, 32
	s_lshl_b32 s0, s1, 10
	s_add_u32 s33, s82, 0x40500000
	s_addc_u32 s38, s83, 0
	s_add_u32 s39, s82, 0x41500000
	s_addc_u32 s40, s83, 0
	v_lshrrev_b32_e32 v1, 5, v194
	s_add_u32 s41, s82, 0x3fd00000
	v_lshlrev_b32_e32 v2, 11, v211
	v_lshlrev_b32_e32 v4, 2, v1
	s_addc_u32 s42, s83, 0
	v_lshl_or_b32 v213, v1, 3, v2
	v_sub_u32_e32 v2, v211, v4
	v_readlane_b32 s4, v249, 54
	s_add_u32 s43, s82, 0x40d00000
	v_mov_b32_e32 v3, 0
	v_add_u32_e32 v214, 0xffffff7f, v2
	v_add_u32_e32 v200, 0xffffff77, v2
	v_add_u32_e32 v202, 0xffffff6f, v2
	v_add_u32_e32 v204, 0xffffff67, v2
	v_lshlrev_b32_e32 v2, 4, v1
	v_readlane_b32 s5, v249, 55
	s_addc_u32 s44, s83, 0
	s_add_i32 s1, 0, 0x8000
	v_lshl_add_u64 v[206:207], s[4:5], 0, v[2:3]
	v_add_u32_e32 v216, s1, v212
	s_add_i32 s1, 0, 0x10000
	v_or_b32_e32 v2, s21, v211
	v_add_u32_e32 v217, s1, v212
	s_add_i32 s1, 0, 0x18000
	v_sub_u32_e32 v219, v2, v4
	v_mbcnt_lo_u32_b32 v2, -1, 0
	v_lshlrev_b32_e32 v198, 4, v0
	v_mov_b32_e32 v199, v3
	v_add_u32_e32 v215, 0, v212
	v_add_u32_e32 v218, s1, v212
	v_mov_b32_e32 v1, v200
	v_mov_b32_e32 v195, v202
	v_mov_b32_e32 v197, v204
	s_mov_b64 s[10:11], 0x2000
	s_mov_b64 s[12:13], 0x4000
	s_mov_b64 s[14:15], 0x6000
	s_mov_b64 s[16:17], 0x8000
	s_mov_b64 s[18:19], 0xa000
	s_mov_b32 s20, 0x3e0293ee
	s_movk_i32 s45, 0xfefe
	s_mov_b32 s46, 0xf149f2ca
	s_mov_b32 s47, 0x41000000
	v_mbcnt_hi_u32_b32 v220, -1, v2
	s_add_i32 s48, s0, 0
	v_mov_b32_e32 v221, 0xf149f2ca
	v_mov_b32_e32 v222, 0x3e0293ee
	s_mov_b32 s49, s2
	s_mov_b32 s50, s2
	s_branch .LBB0_2174

.LBB0_2265:
	s_setprio 2
	s_cmpk_gt_i32 s2, 0xff
	s_cbranch_scc1 .LBB0_2286
	v_readlane_b32 s1, v249, 45
	s_lshl_b32 s0, s1, 16
	s_lshr_b32 s3, s88, 7
	s_and_b32 s20, s0, 0x10000
	s_lshl_b32 s0, s1, 10
	s_add_u32 s21, s82, 0x3f900000
	v_lshrrev_b32_e32 v1, 2, v0
	s_addc_u32 s22, s83, 0
	v_and_b32_e32 v2, 8, v1
	s_add_u32 s23, s82, 0x40900000
	v_lshl_or_b32 v1, v211, 11, v2
	v_lshlrev_b32_e32 v192, 1, v2
	s_addc_u32 s24, s83, 0
	s_add_i32 s1, 0, 0x8000
	v_mbcnt_lo_u32_b32 v2, -1, 0
	v_readlane_b32 s4, v249, 54
	v_add_u32_e32 v197, s1, v212
	s_add_i32 s1, 0, 0x10000
	v_mbcnt_hi_u32_b32 v202, -1, v2
	v_mov_b32_e32 v193, 0
	v_readlane_b32 s5, v249, 55
	v_add_u32_e32 v200, s1, v212
	s_add_i32 s1, 0, 0x18000
	s_add_i32 s29, s0, 0
	v_and_b32_e32 v2, 64, v202
	v_lshlrev_b32_e32 v190, 4, v0
	v_mov_b32_e32 v191, v193
	v_lshl_add_u64 v[198:199], s[4:5], 0, v[192:193]
	v_add_u32_e32 v195, 0, v212
	v_add_u32_e32 v201, s1, v212
	s_lshl_b32 s25, s2, 15
	s_lshl_b32 s26, s90, 15
	s_lshl_b32 s27, s2, 17
	s_lshl_b32 s28, s90, 17
	s_mov_b64 s[0:1], 0x2000
	s_add_i32 s30, s29, 0x2000
	s_add_i32 s31, s29, 0x4000
	s_add_i32 s33, s29, 0x6000
	s_mov_b64 s[4:5], 0x4000
	s_add_i32 s34, s29, 0x8000
	s_mov_b64 s[10:11], 0x6000
	s_add_i32 s35, s29, 0xa000
	s_add_i32 s36, s29, 0xc000
	s_add_i32 s37, s29, 0xe000
	s_mov_b64 s[12:13], 0x8000
	s_add_i32 s38, s29, 0x10000
	s_mov_b64 s[14:15], 0xa000
	s_add_i32 s39, s29, 0x12000
	s_add_i32 s40, s29, 0x14000
	s_add_i32 s41, s29, 0x16000
	s_mov_b64 s[16:17], 0xc000
	s_add_i32 s42, s29, 0x18000
	s_mov_b64 s[18:19], 0xe000
	s_add_i32 s43, s29, 0x1a000
	s_add_i32 s44, s29, 0x1c000
	s_add_i32 s45, s29, 0x1e000
	s_mov_b32 s46, 0xf149f2ca
	s_mov_b32 s47, 0x3e0293ee
	v_xor_b32_e32 v203, 32, v202
	v_add_u32_e32 v204, 64, v2
	s_mov_b32 s48, 0x41000000
	v_mov_b32_e32 v206, 0xf149f2ca
	s_mov_b32 s49, 0x3fb8aa3b
	s_branch .LBB0_2269
